# hand-written QK-norm / Z epilogue (batched cross-lane reductions, fewer VALU ops); redundant s_setprio pairs removed from GEMM K-loops
# baseline (speedup 1.0000x reference)
;     __device__ __forceinline__ void operator()(const AccT& acc, const Unit& u, int wr, int wc, int fr, int fq) const {
;         const int kind = (u.pn + pn_off) >> 3, tile = (u.pn + pn_off) & 7;
;         bf16_t* base = Q + (size_t)kind * ((WS_K - WS_Q) / 2); if (kind == 2) base = Z;
;         const float* g = gq; if (kind == 1) g = gk; const float gs = kind == 0 ? C2 : 1.f;
;         f32x4 gv[2][2];
; #pragma unroll
;         for (int bj = 0; bj < 2; ++bj)
; #pragma unroll
;             for (int n = 0; n < 2; ++n) gv[bj][n] = (kind < 2) ? *(const f32x4*)(g + 32 * bj + 8 * fq + 4 * n) * gs : (f32x4){1.f, 1.f, 1.f, 1.f};
;         const int row0 = u.pm * 256 + wr * 64 + fr;
; #pragma unroll
;         for (int ai = 0; ai < 2; ++ai)
; #pragma unroll
;             for (int m = 0; m < 4; ++m) {
;                 const int row = row0 + ai * 128 + m * 16; float rs = 1.f;
;                 if (kind < 2) { float ss = 0.f;
; #pragma unroll
;                     for (int bj = 0; bj < 2; ++bj)
; #pragma unroll
;                         for (int n = 0; n < 2; ++n) { const f32x4 v = acc[ai][bj][m][n]; ss += (v[0] * v[0] + v[1] * v[1]) + (v[2] * v[2] + v[3] * v[3]); }
;                     ss += __shfl_xor(ss, 16); ss += __shfl_xor(ss, 32); rs = rsqrtf(ss * (1.f / 64.f) + EPS); }
.LBB0_119:
	s_ashr_i32 s66, s64, 3
	s_cmp_eq_u32 s66, 1
	s_cselect_b32 s7, s21, s19
	s_cselect_b32 s6, s20, s18
	s_cmp_lt_u32 s64, 8
	s_cselect_b64 vcc, -1, 0
	v_cndmask_b32_e32 v164, 1.0, v179, vcc
	v_lshl_add_u64 v[166:167], s[6:7], 0, v[136:137]
	s_lshl_b32 s71, s64, 9
	s_and_b32 s71, s71, 0xe00
	s_add_i32 s71, s71, s82
	v_lshl_add_u32 v240, s62, 8, v139
	v_lshlrev_b32_e32 v240, 12, v240
	v_lshl_add_u32 v240, v138, 1, v240
	v_add_u32_e32 v240, s71, v240
	s_lshl_b32 s70, s66, 27
	s_add_u32 s70, s34, s70
	s_addc_u32 s71, s35, 0
	s_cmp_eq_u32 s66, 2
	s_cselect_b32 s70, s28, s70
	s_cselect_b32 s71, s29, s71
	s_cbranch_scc1 .Lqkz_plain_qk
	global_load_dwordx4 v[150:153], v[166:167], off
	global_load_dwordx4 v[200:203], v[166:167], off offset:16
	global_load_dwordx4 v[158:161], v[166:167], off offset:128
	global_load_dwordx4 v[204:207], v[166:167], off offset:144
	v_mul_f32_e32 v220, v124, v124
	v_mul_f32_e32 v221, v120, v120
	v_mul_f32_e32 v222, v116, v116
	v_mul_f32_e32 v223, v112, v112
	v_fmac_f32_e32 v220, v125, v125
	v_fmac_f32_e32 v221, v121, v121
	v_fmac_f32_e32 v222, v117, v117
	v_fmac_f32_e32 v223, v113, v113
	v_fmac_f32_e32 v220, v126, v126
	v_fmac_f32_e32 v221, v122, v122
	v_fmac_f32_e32 v222, v118, v118
	v_fmac_f32_e32 v223, v114, v114
	v_fmac_f32_e32 v220, v127, v127
	v_fmac_f32_e32 v221, v123, v123
	v_fmac_f32_e32 v222, v119, v119
	v_fmac_f32_e32 v223, v115, v115
	v_add_f32_e32 v220, v220, v221
	v_add_f32_e32 v222, v222, v223
	v_add_f32_e32 v184, v220, v222
	v_mul_f32_e32 v220, v108, v108
	v_mul_f32_e32 v221, v104, v104
	v_mul_f32_e32 v222, v100, v100
	v_mul_f32_e32 v223, v96, v96
	v_fmac_f32_e32 v220, v109, v109
	v_fmac_f32_e32 v221, v105, v105
	v_fmac_f32_e32 v222, v101, v101
	v_fmac_f32_e32 v223, v97, v97
	v_fmac_f32_e32 v220, v110, v110
	v_fmac_f32_e32 v221, v106, v106
	v_fmac_f32_e32 v222, v102, v102
	v_fmac_f32_e32 v223, v98, v98
	v_fmac_f32_e32 v220, v111, v111
	v_fmac_f32_e32 v221, v107, v107
	v_fmac_f32_e32 v222, v103, v103
	v_fmac_f32_e32 v223, v99, v99
	v_add_f32_e32 v220, v220, v221
	v_add_f32_e32 v222, v222, v223
	v_add_f32_e32 v185, v220, v222
	v_mul_f32_e32 v220, v92, v92
	v_mul_f32_e32 v221, v88, v88
	v_mul_f32_e32 v222, v84, v84
	v_mul_f32_e32 v223, v80, v80
	v_fmac_f32_e32 v220, v93, v93
	v_fmac_f32_e32 v221, v89, v89
	v_fmac_f32_e32 v222, v85, v85
	v_fmac_f32_e32 v223, v81, v81
	v_fmac_f32_e32 v220, v94, v94
	v_fmac_f32_e32 v221, v90, v90
	v_fmac_f32_e32 v222, v86, v86
	v_fmac_f32_e32 v223, v82, v82
	v_fmac_f32_e32 v220, v95, v95
	v_fmac_f32_e32 v221, v91, v91
	v_fmac_f32_e32 v222, v87, v87
	v_fmac_f32_e32 v223, v83, v83
	v_add_f32_e32 v220, v220, v221
	v_add_f32_e32 v222, v222, v223
	v_add_f32_e32 v186, v220, v222
	v_mul_f32_e32 v220, v76, v76
	v_mul_f32_e32 v221, v72, v72
	v_mul_f32_e32 v222, v68, v68
	v_mul_f32_e32 v223, v64, v64
	v_fmac_f32_e32 v220, v77, v77
	v_fmac_f32_e32 v221, v73, v73
	v_fmac_f32_e32 v222, v69, v69
	v_fmac_f32_e32 v223, v65, v65
	v_fmac_f32_e32 v220, v78, v78
	v_fmac_f32_e32 v221, v74, v74
	v_fmac_f32_e32 v222, v70, v70
	v_fmac_f32_e32 v223, v66, v66
	v_fmac_f32_e32 v220, v79, v79
	v_fmac_f32_e32 v221, v75, v75
	v_fmac_f32_e32 v222, v71, v71
	v_fmac_f32_e32 v223, v67, v67
	v_add_f32_e32 v220, v220, v221
	v_add_f32_e32 v222, v222, v223
	v_add_f32_e32 v187, v220, v222
	v_mul_f32_e32 v220, v60, v60
	v_mul_f32_e32 v221, v56, v56
	v_mul_f32_e32 v222, v52, v52
	v_mul_f32_e32 v223, v48, v48
	v_fmac_f32_e32 v220, v61, v61
	v_fmac_f32_e32 v221, v57, v57
	v_fmac_f32_e32 v222, v53, v53
	v_fmac_f32_e32 v223, v49, v49
	v_fmac_f32_e32 v220, v62, v62
	v_fmac_f32_e32 v221, v58, v58
	v_fmac_f32_e32 v222, v54, v54
	v_fmac_f32_e32 v223, v50, v50
	v_fmac_f32_e32 v220, v63, v63
	v_fmac_f32_e32 v221, v59, v59
	v_fmac_f32_e32 v222, v55, v55
	v_fmac_f32_e32 v223, v51, v51
	v_add_f32_e32 v220, v220, v221
	v_add_f32_e32 v222, v222, v223
	v_add_f32_e32 v188, v220, v222
	v_mul_f32_e32 v220, v44, v44
	v_mul_f32_e32 v221, v40, v40
	v_mul_f32_e32 v222, v36, v36
	v_mul_f32_e32 v223, v32, v32
	v_fmac_f32_e32 v220, v45, v45
	v_fmac_f32_e32 v221, v41, v41
	v_fmac_f32_e32 v222, v37, v37
	v_fmac_f32_e32 v223, v33, v33
	v_fmac_f32_e32 v220, v46, v46
	v_fmac_f32_e32 v221, v42, v42
	v_fmac_f32_e32 v222, v38, v38
	v_fmac_f32_e32 v223, v34, v34
	v_fmac_f32_e32 v220, v47, v47
	v_fmac_f32_e32 v221, v43, v43
	v_fmac_f32_e32 v222, v39, v39
	v_fmac_f32_e32 v223, v35, v35
	v_add_f32_e32 v220, v220, v221
	v_add_f32_e32 v222, v222, v223
	v_add_f32_e32 v189, v220, v222
	v_mul_f32_e32 v220, v28, v28
	v_mul_f32_e32 v221, v24, v24
	v_mul_f32_e32 v222, v20, v20
	v_mul_f32_e32 v223, v16, v16
	v_fmac_f32_e32 v220, v29, v29
	v_fmac_f32_e32 v221, v25, v25
	v_fmac_f32_e32 v222, v21, v21
	v_fmac_f32_e32 v223, v17, v17
	v_fmac_f32_e32 v220, v30, v30
	v_fmac_f32_e32 v221, v26, v26
	v_fmac_f32_e32 v222, v22, v22
	v_fmac_f32_e32 v223, v18, v18
	v_fmac_f32_e32 v220, v31, v31
	v_fmac_f32_e32 v221, v27, v27
	v_fmac_f32_e32 v222, v23, v23
	v_fmac_f32_e32 v223, v19, v19
	v_add_f32_e32 v220, v220, v221
	v_add_f32_e32 v222, v222, v223
	v_add_f32_e32 v190, v220, v222
	v_mul_f32_e32 v220, v12, v12
	v_mul_f32_e32 v221, v8, v8
	v_mul_f32_e32 v222, v4, v4
	v_mul_f32_e32 v223, v0, v0
	v_fmac_f32_e32 v220, v13, v13
	v_fmac_f32_e32 v221, v9, v9
	v_fmac_f32_e32 v222, v5, v5
	v_fmac_f32_e32 v223, v1, v1
	v_fmac_f32_e32 v220, v14, v14
	v_fmac_f32_e32 v221, v10, v10
	v_fmac_f32_e32 v222, v6, v6
	v_fmac_f32_e32 v223, v2, v2
	v_fmac_f32_e32 v220, v15, v15
	v_fmac_f32_e32 v221, v11, v11
	v_fmac_f32_e32 v222, v7, v7
	v_fmac_f32_e32 v223, v3, v3
	v_add_f32_e32 v220, v220, v221
	v_add_f32_e32 v222, v222, v223
	v_add_f32_e32 v191, v220, v222
	ds_bpermute_b32 v192, v173, v184
	ds_bpermute_b32 v193, v173, v185
	ds_bpermute_b32 v194, v173, v186
	ds_bpermute_b32 v195, v173, v187
	ds_bpermute_b32 v196, v173, v188
	ds_bpermute_b32 v197, v173, v189
	ds_bpermute_b32 v198, v173, v190
	ds_bpermute_b32 v199, v173, v191
	v_mov_b32_e32 v165, v164
	s_waitcnt lgkmcnt(7)
; __device__ __forceinline__ u32x4 pack8(const f32x4& a, const f32x4& b) { u32x4 w; w.x = pk2(a[0], a[1]); w.y = pk2(a[2], a[3]); w.z = pk2(b[0], b[1]); w.w = pk2(b[2], b[3]); return w; }
;     __device__ __forceinline__ void operator()(const AccT& acc, const Unit& u, int wr, int wc, int fr, int fq) const {
;     ...
;                     ss += __shfl_xor(ss, 16); ss += __shfl_xor(ss, 32); rs = rsqrtf(ss * (1.f / 64.f) + EPS); }
;                 bf16_t* rp = base + (size_t)row * BR + tile * 256 + 64 * wc + 8 * fq;
; #pragma unroll
;                 for (int bj = 0; bj < 2; ++bj) { const f32x4 v0 = acc[ai][bj][m][0] * rs * gv[bj][0], v1 = acc[ai][bj][m][1] * rs * gv[bj][1];
;                     __builtin_nontemporal_store(pack8(v0, v1), (u32x4*)(rp + 32 * bj)); }
	v_add_f32_e32 v184, v184, v192
	s_waitcnt lgkmcnt(6)
	v_add_f32_e32 v185, v185, v193
	s_waitcnt lgkmcnt(5)
	v_add_f32_e32 v186, v186, v194
	s_waitcnt lgkmcnt(4)
	v_add_f32_e32 v187, v187, v195
	s_waitcnt lgkmcnt(3)
	v_add_f32_e32 v188, v188, v196
	s_waitcnt lgkmcnt(2)
	v_add_f32_e32 v189, v189, v197
	s_waitcnt lgkmcnt(1)
	v_add_f32_e32 v190, v190, v198
	s_waitcnt lgkmcnt(0)
	v_add_f32_e32 v191, v191, v199
	ds_bpermute_b32 v192, v174, v184
	ds_bpermute_b32 v193, v174, v185
	ds_bpermute_b32 v194, v174, v186
	ds_bpermute_b32 v195, v174, v187
	ds_bpermute_b32 v196, v174, v188
	ds_bpermute_b32 v197, v174, v189
	ds_bpermute_b32 v198, v174, v190
	ds_bpermute_b32 v199, v174, v191
	s_waitcnt vmcnt(0)
	v_pk_mul_f32 v[150:151], v[164:165], v[150:151]
	v_pk_mul_f32 v[152:153], v[164:165], v[152:153]
	v_pk_mul_f32 v[148:149], v[164:165], v[200:201]
	v_pk_mul_f32 v[156:157], v[164:165], v[202:203]
	v_pk_mul_f32 v[158:159], v[164:165], v[158:159]
	v_pk_mul_f32 v[160:161], v[164:165], v[160:161]
	v_pk_mul_f32 v[154:155], v[164:165], v[204:205]
	v_pk_mul_f32 v[162:163], v[164:165], v[206:207]
	s_waitcnt lgkmcnt(7)
	v_add_f32_e32 v184, v184, v192
	s_waitcnt lgkmcnt(6)
	v_add_f32_e32 v185, v185, v193
	s_waitcnt lgkmcnt(5)
	v_add_f32_e32 v186, v186, v194
	s_waitcnt lgkmcnt(4)
	v_add_f32_e32 v187, v187, v195
	s_waitcnt lgkmcnt(3)
	v_add_f32_e32 v188, v188, v196
	s_waitcnt lgkmcnt(2)
	v_add_f32_e32 v189, v189, v197
	s_waitcnt lgkmcnt(1)
	v_add_f32_e32 v190, v190, v198
	s_waitcnt lgkmcnt(0)
	v_add_f32_e32 v191, v191, v199
	v_fmamk_f32 v184, v184, 0x3c800000, v178
	v_fmamk_f32 v185, v185, 0x3c800000, v178
	v_fmamk_f32 v186, v186, 0x3c800000, v178
	v_fmamk_f32 v187, v187, 0x3c800000, v178
	v_fmamk_f32 v188, v188, 0x3c800000, v178
	v_fmamk_f32 v189, v189, 0x3c800000, v178
	v_fmamk_f32 v190, v190, 0x3c800000, v178
	v_fmamk_f32 v191, v191, 0x3c800000, v178
	v_rsq_f32_e32 v184, v184
	v_rsq_f32_e32 v185, v185
	v_rsq_f32_e32 v186, v186
	v_rsq_f32_e32 v187, v187
	v_rsq_f32_e32 v188, v188
	v_rsq_f32_e32 v189, v189
	v_rsq_f32_e32 v190, v190
	v_rsq_f32_e32 v191, v191
	s_nop 0
	v_mul_f32_e32 v124, v124, v184
	v_mul_f32_e32 v125, v125, v184
	v_mul_f32_e32 v126, v126, v184
	v_mul_f32_e32 v127, v127, v184
	v_mul_f32_e32 v120, v120, v184
	v_mul_f32_e32 v121, v121, v184
	v_mul_f32_e32 v122, v122, v184
	v_mul_f32_e32 v123, v123, v184
	v_mul_f32_e32 v124, v124, v150
	v_mul_f32_e32 v125, v125, v151
	v_mul_f32_e32 v126, v126, v152
	v_mul_f32_e32 v127, v127, v153
	v_mul_f32_e32 v120, v120, v148
	v_mul_f32_e32 v121, v121, v149
	v_mul_f32_e32 v122, v122, v156
	v_mul_f32_e32 v123, v123, v157
	v_cvt_pk_bf16_f32 v230, v124, v125
	v_cvt_pk_bf16_f32 v231, v126, v127
	v_cvt_pk_bf16_f32 v232, v120, v121
	v_cvt_pk_bf16_f32 v233, v122, v123
	global_store_dwordx4 v240, v[230:233], s[70:71] nt
	v_mul_f32_e32 v116, v116, v184
	v_mul_f32_e32 v117, v117, v184
	v_mul_f32_e32 v118, v118, v184
	v_mul_f32_e32 v119, v119, v184
	v_mul_f32_e32 v112, v112, v184
	v_mul_f32_e32 v113, v113, v184
	v_mul_f32_e32 v114, v114, v184
	v_mul_f32_e32 v115, v115, v184
	v_mul_f32_e32 v116, v116, v158
	v_mul_f32_e32 v117, v117, v159
	v_mul_f32_e32 v118, v118, v160
	v_mul_f32_e32 v119, v119, v161
	v_mul_f32_e32 v112, v112, v154
	v_mul_f32_e32 v113, v113, v155
	v_mul_f32_e32 v114, v114, v162
	v_mul_f32_e32 v115, v115, v163
	v_cvt_pk_bf16_f32 v234, v116, v117
	v_cvt_pk_bf16_f32 v235, v118, v119
	v_cvt_pk_bf16_f32 v236, v112, v113
	v_cvt_pk_bf16_f32 v237, v114, v115
	global_store_dwordx4 v240, v[234:237], s[70:71] offset:64 nt
	v_mul_f32_e32 v108, v108, v185
	v_mul_f32_e32 v109, v109, v185
	v_mul_f32_e32 v110, v110, v185
	v_mul_f32_e32 v111, v111, v185
	v_mul_f32_e32 v104, v104, v185
	v_mul_f32_e32 v105, v105, v185
	v_mul_f32_e32 v106, v106, v185
	v_mul_f32_e32 v107, v107, v185
	v_mul_f32_e32 v108, v108, v150
	v_mul_f32_e32 v109, v109, v151
	v_mul_f32_e32 v110, v110, v152
	v_mul_f32_e32 v111, v111, v153
	v_mul_f32_e32 v104, v104, v148
	v_mul_f32_e32 v105, v105, v149
	v_mul_f32_e32 v106, v106, v156
	v_mul_f32_e32 v107, v107, v157
	v_cvt_pk_bf16_f32 v230, v108, v109
	v_cvt_pk_bf16_f32 v231, v110, v111
	v_cvt_pk_bf16_f32 v232, v104, v105
	v_cvt_pk_bf16_f32 v233, v106, v107
	v_add_u32_e32 v241, 0x10000, v240
	global_store_dwordx4 v241, v[230:233], s[70:71] nt
	v_mul_f32_e32 v100, v100, v185
	v_mul_f32_e32 v101, v101, v185
	v_mul_f32_e32 v102, v102, v185
	v_mul_f32_e32 v103, v103, v185
	v_mul_f32_e32 v96, v96, v185
	v_mul_f32_e32 v97, v97, v185
	v_mul_f32_e32 v98, v98, v185
	v_mul_f32_e32 v99, v99, v185
	v_mul_f32_e32 v100, v100, v158
	v_mul_f32_e32 v101, v101, v159
	v_mul_f32_e32 v102, v102, v160
	v_mul_f32_e32 v103, v103, v161
	v_mul_f32_e32 v96, v96, v154
	v_mul_f32_e32 v97, v97, v155
	v_mul_f32_e32 v98, v98, v162
	v_mul_f32_e32 v99, v99, v163
	v_cvt_pk_bf16_f32 v234, v100, v101
	v_cvt_pk_bf16_f32 v235, v102, v103
	v_cvt_pk_bf16_f32 v236, v96, v97
	v_cvt_pk_bf16_f32 v237, v98, v99
	global_store_dwordx4 v241, v[234:237], s[70:71] offset:64 nt
	v_mul_f32_e32 v92, v92, v186
	v_mul_f32_e32 v93, v93, v186
	v_mul_f32_e32 v94, v94, v186
	v_mul_f32_e32 v95, v95, v186
	v_mul_f32_e32 v88, v88, v186
	v_mul_f32_e32 v89, v89, v186
	v_mul_f32_e32 v90, v90, v186
	v_mul_f32_e32 v91, v91, v186
	v_mul_f32_e32 v92, v92, v150
	v_mul_f32_e32 v93, v93, v151
	v_mul_f32_e32 v94, v94, v152
	v_mul_f32_e32 v95, v95, v153
	v_mul_f32_e32 v88, v88, v148
	v_mul_f32_e32 v89, v89, v149
	v_mul_f32_e32 v90, v90, v156
	v_mul_f32_e32 v91, v91, v157
	v_cvt_pk_bf16_f32 v230, v92, v93
	v_cvt_pk_bf16_f32 v231, v94, v95
	v_cvt_pk_bf16_f32 v232, v88, v89
	v_cvt_pk_bf16_f32 v233, v90, v91
	v_add_u32_e32 v241, 0x20000, v240
	global_store_dwordx4 v241, v[230:233], s[70:71] nt
; __device__ __forceinline__ u32x4 pack8(const f32x4& a, const f32x4& b) { u32x4 w; w.x = pk2(a[0], a[1]); w.y = pk2(a[2], a[3]); w.z = pk2(b[0], b[1]); w.w = pk2(b[2], b[3]); return w; }
;     __device__ __forceinline__ void operator()(const AccT& acc, const Unit& u, int wr, int wc, int fr, int fq) const {
;     ...
;                 bf16_t* rp = base + (size_t)row * BR + tile * 256 + 64 * wc + 8 * fq;
; #pragma unroll
;                 for (int bj = 0; bj < 2; ++bj) { const f32x4 v0 = acc[ai][bj][m][0] * rs * gv[bj][0], v1 = acc[ai][bj][m][1] * rs * gv[bj][1];
;                     __builtin_nontemporal_store(pack8(v0, v1), (u32x4*)(rp + 32 * bj)); }
	v_mul_f32_e32 v84, v84, v186
	v_mul_f32_e32 v85, v85, v186
	v_mul_f32_e32 v86, v86, v186
	v_mul_f32_e32 v87, v87, v186
	v_mul_f32_e32 v80, v80, v186
	v_mul_f32_e32 v81, v81, v186
	v_mul_f32_e32 v82, v82, v186
	v_mul_f32_e32 v83, v83, v186
	v_mul_f32_e32 v84, v84, v158
	v_mul_f32_e32 v85, v85, v159
	v_mul_f32_e32 v86, v86, v160
	v_mul_f32_e32 v87, v87, v161
	v_mul_f32_e32 v80, v80, v154
	v_mul_f32_e32 v81, v81, v155
	v_mul_f32_e32 v82, v82, v162
	v_mul_f32_e32 v83, v83, v163
	v_cvt_pk_bf16_f32 v234, v84, v85
	v_cvt_pk_bf16_f32 v235, v86, v87
	v_cvt_pk_bf16_f32 v236, v80, v81
	v_cvt_pk_bf16_f32 v237, v82, v83
	global_store_dwordx4 v241, v[234:237], s[70:71] offset:64 nt
	v_mul_f32_e32 v76, v76, v187
	v_mul_f32_e32 v77, v77, v187
	v_mul_f32_e32 v78, v78, v187
	v_mul_f32_e32 v79, v79, v187
	v_mul_f32_e32 v72, v72, v187
	v_mul_f32_e32 v73, v73, v187
	v_mul_f32_e32 v74, v74, v187
	v_mul_f32_e32 v75, v75, v187
	v_mul_f32_e32 v76, v76, v150
	v_mul_f32_e32 v77, v77, v151
	v_mul_f32_e32 v78, v78, v152
	v_mul_f32_e32 v79, v79, v153
	v_mul_f32_e32 v72, v72, v148
	v_mul_f32_e32 v73, v73, v149
	v_mul_f32_e32 v74, v74, v156
	v_mul_f32_e32 v75, v75, v157
	v_cvt_pk_bf16_f32 v230, v76, v77
	v_cvt_pk_bf16_f32 v231, v78, v79
	v_cvt_pk_bf16_f32 v232, v72, v73
	v_cvt_pk_bf16_f32 v233, v74, v75
	v_add_u32_e32 v241, 0x30000, v240
	global_store_dwordx4 v241, v[230:233], s[70:71] nt
	v_mul_f32_e32 v68, v68, v187
	v_mul_f32_e32 v69, v69, v187
	v_mul_f32_e32 v70, v70, v187
	v_mul_f32_e32 v71, v71, v187
	v_mul_f32_e32 v64, v64, v187
	v_mul_f32_e32 v65, v65, v187
	v_mul_f32_e32 v66, v66, v187
	v_mul_f32_e32 v67, v67, v187
	v_mul_f32_e32 v68, v68, v158
	v_mul_f32_e32 v69, v69, v159
	v_mul_f32_e32 v70, v70, v160
	v_mul_f32_e32 v71, v71, v161
	v_mul_f32_e32 v64, v64, v154
	v_mul_f32_e32 v65, v65, v155
	v_mul_f32_e32 v66, v66, v162
	v_mul_f32_e32 v67, v67, v163
	v_cvt_pk_bf16_f32 v234, v68, v69
	v_cvt_pk_bf16_f32 v235, v70, v71
	v_cvt_pk_bf16_f32 v236, v64, v65
	v_cvt_pk_bf16_f32 v237, v66, v67
	global_store_dwordx4 v241, v[234:237], s[70:71] offset:64 nt
	v_mul_f32_e32 v60, v60, v188
	v_mul_f32_e32 v61, v61, v188
	v_mul_f32_e32 v62, v62, v188
	v_mul_f32_e32 v63, v63, v188
	v_mul_f32_e32 v56, v56, v188
	v_mul_f32_e32 v57, v57, v188
	v_mul_f32_e32 v58, v58, v188
	v_mul_f32_e32 v59, v59, v188
	v_mul_f32_e32 v60, v60, v150
	v_mul_f32_e32 v61, v61, v151
	v_mul_f32_e32 v62, v62, v152
	v_mul_f32_e32 v63, v63, v153
	v_mul_f32_e32 v56, v56, v148
	v_mul_f32_e32 v57, v57, v149
	v_mul_f32_e32 v58, v58, v156
	v_mul_f32_e32 v59, v59, v157
	v_cvt_pk_bf16_f32 v230, v60, v61
	v_cvt_pk_bf16_f32 v231, v62, v63
	v_cvt_pk_bf16_f32 v232, v56, v57
	v_cvt_pk_bf16_f32 v233, v58, v59
	v_add_u32_e32 v241, 0x80000, v240
	global_store_dwordx4 v241, v[230:233], s[70:71] nt
	v_mul_f32_e32 v52, v52, v188
	v_mul_f32_e32 v53, v53, v188
	v_mul_f32_e32 v54, v54, v188
	v_mul_f32_e32 v55, v55, v188
	v_mul_f32_e32 v48, v48, v188
	v_mul_f32_e32 v49, v49, v188
	v_mul_f32_e32 v50, v50, v188
	v_mul_f32_e32 v51, v51, v188
	v_mul_f32_e32 v52, v52, v158
	v_mul_f32_e32 v53, v53, v159
	v_mul_f32_e32 v54, v54, v160
	v_mul_f32_e32 v55, v55, v161
	v_mul_f32_e32 v48, v48, v154
	v_mul_f32_e32 v49, v49, v155
	v_mul_f32_e32 v50, v50, v162
	v_mul_f32_e32 v51, v51, v163
	v_cvt_pk_bf16_f32 v234, v52, v53
	v_cvt_pk_bf16_f32 v235, v54, v55
	v_cvt_pk_bf16_f32 v236, v48, v49
	v_cvt_pk_bf16_f32 v237, v50, v51
	global_store_dwordx4 v241, v[234:237], s[70:71] offset:64 nt
	v_mul_f32_e32 v44, v44, v189
	v_mul_f32_e32 v45, v45, v189
	v_mul_f32_e32 v46, v46, v189
	v_mul_f32_e32 v47, v47, v189
	v_mul_f32_e32 v40, v40, v189
	v_mul_f32_e32 v41, v41, v189
	v_mul_f32_e32 v42, v42, v189
	v_mul_f32_e32 v43, v43, v189
	v_mul_f32_e32 v44, v44, v150
	v_mul_f32_e32 v45, v45, v151
	v_mul_f32_e32 v46, v46, v152
	v_mul_f32_e32 v47, v47, v153
	v_mul_f32_e32 v40, v40, v148
	v_mul_f32_e32 v41, v41, v149
	v_mul_f32_e32 v42, v42, v156
	v_mul_f32_e32 v43, v43, v157
	v_cvt_pk_bf16_f32 v230, v44, v45
	v_cvt_pk_bf16_f32 v231, v46, v47
	v_cvt_pk_bf16_f32 v232, v40, v41
	v_cvt_pk_bf16_f32 v233, v42, v43
	v_add_u32_e32 v241, 0x90000, v240
	global_store_dwordx4 v241, v[230:233], s[70:71] nt
	v_mul_f32_e32 v36, v36, v189
	v_mul_f32_e32 v37, v37, v189
	v_mul_f32_e32 v38, v38, v189
	v_mul_f32_e32 v39, v39, v189
	v_mul_f32_e32 v32, v32, v189
	v_mul_f32_e32 v33, v33, v189
	v_mul_f32_e32 v34, v34, v189
	v_mul_f32_e32 v35, v35, v189
	v_mul_f32_e32 v36, v36, v158
	v_mul_f32_e32 v37, v37, v159
	v_mul_f32_e32 v38, v38, v160
	v_mul_f32_e32 v39, v39, v161
	v_mul_f32_e32 v32, v32, v154
	v_mul_f32_e32 v33, v33, v155
	v_mul_f32_e32 v34, v34, v162
	v_mul_f32_e32 v35, v35, v163
	v_cvt_pk_bf16_f32 v234, v36, v37
	v_cvt_pk_bf16_f32 v235, v38, v39
	v_cvt_pk_bf16_f32 v236, v32, v33
	v_cvt_pk_bf16_f32 v237, v34, v35
	global_store_dwordx4 v241, v[234:237], s[70:71] offset:64 nt
	v_mul_f32_e32 v28, v28, v190
	v_mul_f32_e32 v29, v29, v190
	v_mul_f32_e32 v30, v30, v190
	v_mul_f32_e32 v31, v31, v190
	v_mul_f32_e32 v24, v24, v190
	v_mul_f32_e32 v25, v25, v190
	v_mul_f32_e32 v26, v26, v190
	v_mul_f32_e32 v27, v27, v190
	v_mul_f32_e32 v28, v28, v150
	v_mul_f32_e32 v29, v29, v151
	v_mul_f32_e32 v30, v30, v152
	v_mul_f32_e32 v31, v31, v153
	v_mul_f32_e32 v24, v24, v148
	v_mul_f32_e32 v25, v25, v149
	v_mul_f32_e32 v26, v26, v156
	v_mul_f32_e32 v27, v27, v157
	v_cvt_pk_bf16_f32 v230, v28, v29
	v_cvt_pk_bf16_f32 v231, v30, v31
	v_cvt_pk_bf16_f32 v232, v24, v25
	v_cvt_pk_bf16_f32 v233, v26, v27
	v_add_u32_e32 v241, 0xa0000, v240
	global_store_dwordx4 v241, v[230:233], s[70:71] nt
	v_mul_f32_e32 v20, v20, v190
; __device__ __forceinline__ u32x4 pack8(const f32x4& a, const f32x4& b) { u32x4 w; w.x = pk2(a[0], a[1]); w.y = pk2(a[2], a[3]); w.z = pk2(b[0], b[1]); w.w = pk2(b[2], b[3]); return w; }
;     __device__ __forceinline__ void operator()(const AccT& acc, const Unit& u, int wr, int wc, int fr, int fq) const {
;     ...
;                 bf16_t* rp = base + (size_t)row * BR + tile * 256 + 64 * wc + 8 * fq;
; #pragma unroll
;                 for (int bj = 0; bj < 2; ++bj) { const f32x4 v0 = acc[ai][bj][m][0] * rs * gv[bj][0], v1 = acc[ai][bj][m][1] * rs * gv[bj][1];
;                     __builtin_nontemporal_store(pack8(v0, v1), (u32x4*)(rp + 32 * bj)); }
;             }
	v_mul_f32_e32 v21, v21, v190
	v_mul_f32_e32 v22, v22, v190
	v_mul_f32_e32 v23, v23, v190
	v_mul_f32_e32 v16, v16, v190
	v_mul_f32_e32 v17, v17, v190
	v_mul_f32_e32 v18, v18, v190
	v_mul_f32_e32 v19, v19, v190
	v_mul_f32_e32 v20, v20, v158
	v_mul_f32_e32 v21, v21, v159
	v_mul_f32_e32 v22, v22, v160
	v_mul_f32_e32 v23, v23, v161
	v_mul_f32_e32 v16, v16, v154
	v_mul_f32_e32 v17, v17, v155
	v_mul_f32_e32 v18, v18, v162
	v_mul_f32_e32 v19, v19, v163
	v_cvt_pk_bf16_f32 v234, v20, v21
	v_cvt_pk_bf16_f32 v235, v22, v23
	v_cvt_pk_bf16_f32 v236, v16, v17
	v_cvt_pk_bf16_f32 v237, v18, v19
	global_store_dwordx4 v241, v[234:237], s[70:71] offset:64 nt
	v_mul_f32_e32 v12, v12, v191
	v_mul_f32_e32 v13, v13, v191
	v_mul_f32_e32 v14, v14, v191
	v_mul_f32_e32 v15, v15, v191
	v_mul_f32_e32 v8, v8, v191
	v_mul_f32_e32 v9, v9, v191
	v_mul_f32_e32 v10, v10, v191
	v_mul_f32_e32 v11, v11, v191
	v_mul_f32_e32 v12, v12, v150
	v_mul_f32_e32 v13, v13, v151
	v_mul_f32_e32 v14, v14, v152
	v_mul_f32_e32 v15, v15, v153
	v_mul_f32_e32 v8, v8, v148
	v_mul_f32_e32 v9, v9, v149
	v_mul_f32_e32 v10, v10, v156
	v_mul_f32_e32 v11, v11, v157
	v_cvt_pk_bf16_f32 v230, v12, v13
	v_cvt_pk_bf16_f32 v231, v14, v15
	v_cvt_pk_bf16_f32 v232, v8, v9
	v_cvt_pk_bf16_f32 v233, v10, v11
	v_add_u32_e32 v241, 0xb0000, v240
	global_store_dwordx4 v241, v[230:233], s[70:71] nt
	v_mul_f32_e32 v4, v4, v191
	v_mul_f32_e32 v5, v5, v191
	v_mul_f32_e32 v6, v6, v191
	v_mul_f32_e32 v7, v7, v191
	v_mul_f32_e32 v0, v0, v191
	v_mul_f32_e32 v1, v1, v191
	v_mul_f32_e32 v2, v2, v191
	v_mul_f32_e32 v3, v3, v191
	v_mul_f32_e32 v4, v4, v158
	v_mul_f32_e32 v5, v5, v159
	v_mul_f32_e32 v6, v6, v160
	v_mul_f32_e32 v7, v7, v161
	v_mul_f32_e32 v0, v0, v154
	v_mul_f32_e32 v1, v1, v155
	v_mul_f32_e32 v2, v2, v162
	v_mul_f32_e32 v3, v3, v163
	v_cvt_pk_bf16_f32 v234, v4, v5
	v_cvt_pk_bf16_f32 v235, v6, v7
	v_cvt_pk_bf16_f32 v236, v0, v1
	v_cvt_pk_bf16_f32 v237, v2, v3
	global_store_dwordx4 v241, v[234:237], s[70:71] offset:64 nt
	s_branch .Lqkz_done_qk
.Lqkz_plain_qk:
	v_cvt_pk_bf16_f32 v230, v124, v125
	v_cvt_pk_bf16_f32 v231, v126, v127
	v_cvt_pk_bf16_f32 v232, v120, v121
	v_cvt_pk_bf16_f32 v233, v122, v123
	global_store_dwordx4 v240, v[230:233], s[70:71] nt
	v_cvt_pk_bf16_f32 v234, v116, v117
	v_cvt_pk_bf16_f32 v235, v118, v119
	v_cvt_pk_bf16_f32 v236, v112, v113
	v_cvt_pk_bf16_f32 v237, v114, v115
	global_store_dwordx4 v240, v[234:237], s[70:71] offset:64 nt
	v_cvt_pk_bf16_f32 v230, v108, v109
	v_cvt_pk_bf16_f32 v231, v110, v111
	v_cvt_pk_bf16_f32 v232, v104, v105
	v_cvt_pk_bf16_f32 v233, v106, v107
	v_add_u32_e32 v241, 0x10000, v240
	global_store_dwordx4 v241, v[230:233], s[70:71] nt
	v_cvt_pk_bf16_f32 v234, v100, v101
	v_cvt_pk_bf16_f32 v235, v102, v103
	v_cvt_pk_bf16_f32 v236, v96, v97
	v_cvt_pk_bf16_f32 v237, v98, v99
	global_store_dwordx4 v241, v[234:237], s[70:71] offset:64 nt
	v_cvt_pk_bf16_f32 v230, v92, v93
	v_cvt_pk_bf16_f32 v231, v94, v95
	v_cvt_pk_bf16_f32 v232, v88, v89
	v_cvt_pk_bf16_f32 v233, v90, v91
	v_add_u32_e32 v241, 0x20000, v240
	global_store_dwordx4 v241, v[230:233], s[70:71] nt
	v_cvt_pk_bf16_f32 v234, v84, v85
	v_cvt_pk_bf16_f32 v235, v86, v87
	v_cvt_pk_bf16_f32 v236, v80, v81
	v_cvt_pk_bf16_f32 v237, v82, v83
	global_store_dwordx4 v241, v[234:237], s[70:71] offset:64 nt
	v_cvt_pk_bf16_f32 v230, v76, v77
	v_cvt_pk_bf16_f32 v231, v78, v79
	v_cvt_pk_bf16_f32 v232, v72, v73
	v_cvt_pk_bf16_f32 v233, v74, v75
	v_add_u32_e32 v241, 0x30000, v240
	global_store_dwordx4 v241, v[230:233], s[70:71] nt
	v_cvt_pk_bf16_f32 v234, v68, v69
	v_cvt_pk_bf16_f32 v235, v70, v71
	v_cvt_pk_bf16_f32 v236, v64, v65
	v_cvt_pk_bf16_f32 v237, v66, v67
	global_store_dwordx4 v241, v[234:237], s[70:71] offset:64 nt
	v_cvt_pk_bf16_f32 v230, v60, v61
	v_cvt_pk_bf16_f32 v231, v62, v63
	v_cvt_pk_bf16_f32 v232, v56, v57
	v_cvt_pk_bf16_f32 v233, v58, v59
	v_add_u32_e32 v241, 0x80000, v240
	global_store_dwordx4 v241, v[230:233], s[70:71] nt
	v_cvt_pk_bf16_f32 v234, v52, v53
	v_cvt_pk_bf16_f32 v235, v54, v55
	v_cvt_pk_bf16_f32 v236, v48, v49
	v_cvt_pk_bf16_f32 v237, v50, v51
	global_store_dwordx4 v241, v[234:237], s[70:71] offset:64 nt
	v_cvt_pk_bf16_f32 v230, v44, v45
	v_cvt_pk_bf16_f32 v231, v46, v47
	v_cvt_pk_bf16_f32 v232, v40, v41
	v_cvt_pk_bf16_f32 v233, v42, v43
	v_add_u32_e32 v241, 0x90000, v240
	global_store_dwordx4 v241, v[230:233], s[70:71] nt
	v_cvt_pk_bf16_f32 v234, v36, v37
	v_cvt_pk_bf16_f32 v235, v38, v39
	v_cvt_pk_bf16_f32 v236, v32, v33
	v_cvt_pk_bf16_f32 v237, v34, v35
	global_store_dwordx4 v241, v[234:237], s[70:71] offset:64 nt
	v_cvt_pk_bf16_f32 v230, v28, v29
	v_cvt_pk_bf16_f32 v231, v30, v31
	v_cvt_pk_bf16_f32 v232, v24, v25
	v_cvt_pk_bf16_f32 v233, v26, v27
	v_add_u32_e32 v241, 0xa0000, v240
	global_store_dwordx4 v241, v[230:233], s[70:71] nt
	v_cvt_pk_bf16_f32 v234, v20, v21
	v_cvt_pk_bf16_f32 v235, v22, v23
	v_cvt_pk_bf16_f32 v236, v16, v17
	v_cvt_pk_bf16_f32 v237, v18, v19
	global_store_dwordx4 v241, v[234:237], s[70:71] offset:64 nt
	v_cvt_pk_bf16_f32 v230, v12, v13
	v_cvt_pk_bf16_f32 v231, v14, v15
	v_cvt_pk_bf16_f32 v232, v8, v9
	v_cvt_pk_bf16_f32 v233, v10, v11
	v_add_u32_e32 v241, 0xb0000, v240
	global_store_dwordx4 v241, v[230:233], s[70:71] nt
	v_cvt_pk_bf16_f32 v234, v4, v5
	v_cvt_pk_bf16_f32 v235, v6, v7
	v_cvt_pk_bf16_f32 v236, v0, v1
	v_cvt_pk_bf16_f32 v237, v2, v3
	global_store_dwordx4 v241, v[234:237], s[70:71] offset:64 nt
.Lqkz_done_qk:
	s_andn2_b64 vcc, exec, s[0:1]
	s_mov_b64 s[0:1], -1
	s_cbranch_vccnz .LBB0_108
	s_andn2_b64 vcc, exec, s[8:9]
	s_cbranch_vccnz .LBB0_107
	s_barrier
	s_branch .LBB0_107

;     __device__ __forceinline__ void operator()(const AccT& acc, const Unit& u, int wr, int wc, int fr, int fq) const {
;         const int kind = (u.pn + pn_off) >> 3, tile = (u.pn + pn_off) & 7;
;         bf16_t* base = Q + (size_t)kind * ((WS_K - WS_Q) / 2); if (kind == 2) base = Z;
;         const float* g = gq; if (kind == 1) g = gk; const float gs = kind == 0 ? C2 : 1.f;
;         f32x4 gv[2][2];
; #pragma unroll
;         for (int bj = 0; bj < 2; ++bj)
; #pragma unroll
;             for (int n = 0; n < 2; ++n) gv[bj][n] = (kind < 2) ? *(const f32x4*)(g + 32 * bj + 8 * fq + 4 * n) * gs : (f32x4){1.f, 1.f, 1.f, 1.f};
;         const int row0 = u.pm * 256 + wr * 64 + fr;
; #pragma unroll
;         for (int ai = 0; ai < 2; ++ai)
; #pragma unroll
;             for (int m = 0; m < 4; ++m) {
;                 const int row = row0 + ai * 128 + m * 16; float rs = 1.f;
;                 if (kind < 2) { float ss = 0.f;
; #pragma unroll
;                     for (int bj = 0; bj < 2; ++bj)
; #pragma unroll
;                         for (int n = 0; n < 2; ++n) { const f32x4 v = acc[ai][bj][m][n]; ss += (v[0] * v[0] + v[1] * v[1]) + (v[2] * v[2] + v[3] * v[3]); }
;                     ss += __shfl_xor(ss, 16); ss += __shfl_xor(ss, 32); rs = rsqrtf(ss * (1.f / 64.f) + EPS); }
.LBB0_169:
	s_add_i32 s72, s66, 16
	s_ashr_i32 s53, s72, 3
	s_cmp_eq_u32 s53, 1
	s_cselect_b32 s7, s21, s19
	s_cselect_b32 s6, s20, s18
	s_cmp_lt_u32 s72, 8
	s_cselect_b64 vcc, -1, 0
	v_cndmask_b32_e32 v164, 1.0, v179, vcc
	v_lshl_add_u64 v[166:167], s[6:7], 0, v[136:137]
	s_lshl_b32 s73, s72, 9
	s_and_b32 s73, s73, 0xe00
	s_add_i32 s73, s73, s86
	v_lshl_add_u32 v240, s64, 8, v139
	v_lshlrev_b32_e32 v240, 12, v240
	v_lshl_add_u32 v240, v138, 1, v240
	v_add_u32_e32 v240, s73, v240
	s_lshl_b32 s72, s53, 27
	s_add_u32 s72, s34, s72
	s_addc_u32 s73, s35, 0
	s_cmp_eq_u32 s53, 2
	s_cselect_b32 s72, s28, s72
	s_cselect_b32 s73, s29, s73
	s_cbranch_scc1 .Lqkz_plain_z
	global_load_dwordx4 v[150:153], v[166:167], off
	global_load_dwordx4 v[200:203], v[166:167], off offset:16
	global_load_dwordx4 v[158:161], v[166:167], off offset:128
	global_load_dwordx4 v[204:207], v[166:167], off offset:144
	v_mul_f32_e32 v220, v124, v124
	v_mul_f32_e32 v221, v120, v120
	v_mul_f32_e32 v222, v116, v116
	v_mul_f32_e32 v223, v112, v112
	v_fmac_f32_e32 v220, v125, v125
	v_fmac_f32_e32 v221, v121, v121
	v_fmac_f32_e32 v222, v117, v117
	v_fmac_f32_e32 v223, v113, v113
	v_fmac_f32_e32 v220, v126, v126
	v_fmac_f32_e32 v221, v122, v122
	v_fmac_f32_e32 v222, v118, v118
	v_fmac_f32_e32 v223, v114, v114
	v_fmac_f32_e32 v220, v127, v127
	v_fmac_f32_e32 v221, v123, v123
	v_fmac_f32_e32 v222, v119, v119
	v_fmac_f32_e32 v223, v115, v115
	v_add_f32_e32 v220, v220, v221
	v_add_f32_e32 v222, v222, v223
	v_add_f32_e32 v184, v220, v222
	v_mul_f32_e32 v220, v108, v108
	v_mul_f32_e32 v221, v104, v104
	v_mul_f32_e32 v222, v100, v100
	v_mul_f32_e32 v223, v96, v96
	v_fmac_f32_e32 v220, v109, v109
	v_fmac_f32_e32 v221, v105, v105
	v_fmac_f32_e32 v222, v101, v101
	v_fmac_f32_e32 v223, v97, v97
	v_fmac_f32_e32 v220, v110, v110
	v_fmac_f32_e32 v221, v106, v106
	v_fmac_f32_e32 v222, v102, v102
	v_fmac_f32_e32 v223, v98, v98
	v_fmac_f32_e32 v220, v111, v111
	v_fmac_f32_e32 v221, v107, v107
	v_fmac_f32_e32 v222, v103, v103
	v_fmac_f32_e32 v223, v99, v99
	v_add_f32_e32 v220, v220, v221
	v_add_f32_e32 v222, v222, v223
	v_add_f32_e32 v185, v220, v222
	v_mul_f32_e32 v220, v92, v92
	v_mul_f32_e32 v221, v88, v88
	v_mul_f32_e32 v222, v84, v84
	v_mul_f32_e32 v223, v80, v80
	v_fmac_f32_e32 v220, v93, v93
	v_fmac_f32_e32 v221, v89, v89
	v_fmac_f32_e32 v222, v85, v85
	v_fmac_f32_e32 v223, v81, v81
	v_fmac_f32_e32 v220, v94, v94
	v_fmac_f32_e32 v221, v90, v90
	v_fmac_f32_e32 v222, v86, v86
	v_fmac_f32_e32 v223, v82, v82
	v_fmac_f32_e32 v220, v95, v95
	v_fmac_f32_e32 v221, v91, v91
	v_fmac_f32_e32 v222, v87, v87
	v_fmac_f32_e32 v223, v83, v83
	v_add_f32_e32 v220, v220, v221
	v_add_f32_e32 v222, v222, v223
	v_add_f32_e32 v186, v220, v222
	v_mul_f32_e32 v220, v76, v76
	v_mul_f32_e32 v221, v72, v72
	v_mul_f32_e32 v222, v68, v68
	v_mul_f32_e32 v223, v64, v64
	v_fmac_f32_e32 v220, v77, v77
	v_fmac_f32_e32 v221, v73, v73
	v_fmac_f32_e32 v222, v69, v69
	v_fmac_f32_e32 v223, v65, v65
	v_fmac_f32_e32 v220, v78, v78
	v_fmac_f32_e32 v221, v74, v74
	v_fmac_f32_e32 v222, v70, v70
	v_fmac_f32_e32 v223, v66, v66
	v_fmac_f32_e32 v220, v79, v79
	v_fmac_f32_e32 v221, v75, v75
	v_fmac_f32_e32 v222, v71, v71
	v_fmac_f32_e32 v223, v67, v67
	v_add_f32_e32 v220, v220, v221
	v_add_f32_e32 v222, v222, v223
	v_add_f32_e32 v187, v220, v222
	v_mul_f32_e32 v220, v60, v60
	v_mul_f32_e32 v221, v56, v56
	v_mul_f32_e32 v222, v52, v52
	v_mul_f32_e32 v223, v48, v48
	v_fmac_f32_e32 v220, v61, v61
	v_fmac_f32_e32 v221, v57, v57
	v_fmac_f32_e32 v222, v53, v53
	v_fmac_f32_e32 v223, v49, v49
	v_fmac_f32_e32 v220, v62, v62
	v_fmac_f32_e32 v221, v58, v58
	v_fmac_f32_e32 v222, v54, v54
	v_fmac_f32_e32 v223, v50, v50
	v_fmac_f32_e32 v220, v63, v63
	v_fmac_f32_e32 v221, v59, v59
	v_fmac_f32_e32 v222, v55, v55
	v_fmac_f32_e32 v223, v51, v51
	v_add_f32_e32 v220, v220, v221
	v_add_f32_e32 v222, v222, v223
	v_add_f32_e32 v188, v220, v222
	v_mul_f32_e32 v220, v44, v44
	v_mul_f32_e32 v221, v40, v40
	v_mul_f32_e32 v222, v36, v36
	v_mul_f32_e32 v223, v32, v32
	v_fmac_f32_e32 v220, v45, v45
	v_fmac_f32_e32 v221, v41, v41
	v_fmac_f32_e32 v222, v37, v37
	v_fmac_f32_e32 v223, v33, v33
	v_fmac_f32_e32 v220, v46, v46
	v_fmac_f32_e32 v221, v42, v42
	v_fmac_f32_e32 v222, v38, v38
	v_fmac_f32_e32 v223, v34, v34
	v_fmac_f32_e32 v220, v47, v47
	v_fmac_f32_e32 v221, v43, v43
	v_fmac_f32_e32 v222, v39, v39
	v_fmac_f32_e32 v223, v35, v35
	v_add_f32_e32 v220, v220, v221
	v_add_f32_e32 v222, v222, v223
	v_add_f32_e32 v189, v220, v222
	v_mul_f32_e32 v220, v28, v28
	v_mul_f32_e32 v221, v24, v24
	v_mul_f32_e32 v222, v20, v20
	v_mul_f32_e32 v223, v16, v16
	v_fmac_f32_e32 v220, v29, v29
	v_fmac_f32_e32 v221, v25, v25
	v_fmac_f32_e32 v222, v21, v21
	v_fmac_f32_e32 v223, v17, v17
	v_fmac_f32_e32 v220, v30, v30
	v_fmac_f32_e32 v221, v26, v26
	v_fmac_f32_e32 v222, v22, v22
	v_fmac_f32_e32 v223, v18, v18
	v_fmac_f32_e32 v220, v31, v31
	v_fmac_f32_e32 v221, v27, v27
	v_fmac_f32_e32 v222, v23, v23
	v_fmac_f32_e32 v223, v19, v19
	v_add_f32_e32 v220, v220, v221
	v_add_f32_e32 v222, v222, v223
	v_add_f32_e32 v190, v220, v222
	v_mul_f32_e32 v220, v12, v12
	v_mul_f32_e32 v221, v8, v8
	v_mul_f32_e32 v222, v4, v4
	v_mul_f32_e32 v223, v0, v0
	v_fmac_f32_e32 v220, v13, v13
	v_fmac_f32_e32 v221, v9, v9
	v_fmac_f32_e32 v222, v5, v5
	v_fmac_f32_e32 v223, v1, v1
	v_fmac_f32_e32 v220, v14, v14
	v_fmac_f32_e32 v221, v10, v10
	v_fmac_f32_e32 v222, v6, v6
	v_fmac_f32_e32 v223, v2, v2
	v_fmac_f32_e32 v220, v15, v15
	v_fmac_f32_e32 v221, v11, v11
	v_fmac_f32_e32 v222, v7, v7
	v_fmac_f32_e32 v223, v3, v3
	v_add_f32_e32 v220, v220, v221
	v_add_f32_e32 v222, v222, v223
	v_add_f32_e32 v191, v220, v222
	ds_bpermute_b32 v192, v173, v184
	ds_bpermute_b32 v193, v173, v185
	ds_bpermute_b32 v194, v173, v186
	ds_bpermute_b32 v195, v173, v187
	ds_bpermute_b32 v196, v173, v188
	ds_bpermute_b32 v197, v173, v189
	ds_bpermute_b32 v198, v173, v190
	ds_bpermute_b32 v199, v173, v191
	v_mov_b32_e32 v165, v164
	s_waitcnt lgkmcnt(7)
; __device__ __forceinline__ u32x4 pack8(const f32x4& a, const f32x4& b) { u32x4 w; w.x = pk2(a[0], a[1]); w.y = pk2(a[2], a[3]); w.z = pk2(b[0], b[1]); w.w = pk2(b[2], b[3]); return w; }
;     __device__ __forceinline__ void operator()(const AccT& acc, const Unit& u, int wr, int wc, int fr, int fq) const {
;     ...
;                     ss += __shfl_xor(ss, 16); ss += __shfl_xor(ss, 32); rs = rsqrtf(ss * (1.f / 64.f) + EPS); }
;                 bf16_t* rp = base + (size_t)row * BR + tile * 256 + 64 * wc + 8 * fq;
; #pragma unroll
;                 for (int bj = 0; bj < 2; ++bj) { const f32x4 v0 = acc[ai][bj][m][0] * rs * gv[bj][0], v1 = acc[ai][bj][m][1] * rs * gv[bj][1];
;                     __builtin_nontemporal_store(pack8(v0, v1), (u32x4*)(rp + 32 * bj)); }
	v_add_f32_e32 v184, v184, v192
	s_waitcnt lgkmcnt(6)
	v_add_f32_e32 v185, v185, v193
	s_waitcnt lgkmcnt(5)
	v_add_f32_e32 v186, v186, v194
	s_waitcnt lgkmcnt(4)
	v_add_f32_e32 v187, v187, v195
	s_waitcnt lgkmcnt(3)
	v_add_f32_e32 v188, v188, v196
	s_waitcnt lgkmcnt(2)
	v_add_f32_e32 v189, v189, v197
	s_waitcnt lgkmcnt(1)
	v_add_f32_e32 v190, v190, v198
	s_waitcnt lgkmcnt(0)
	v_add_f32_e32 v191, v191, v199
	ds_bpermute_b32 v192, v174, v184
	ds_bpermute_b32 v193, v174, v185
	ds_bpermute_b32 v194, v174, v186
	ds_bpermute_b32 v195, v174, v187
	ds_bpermute_b32 v196, v174, v188
	ds_bpermute_b32 v197, v174, v189
	ds_bpermute_b32 v198, v174, v190
	ds_bpermute_b32 v199, v174, v191
	s_waitcnt vmcnt(0)
	v_pk_mul_f32 v[150:151], v[164:165], v[150:151]
	v_pk_mul_f32 v[152:153], v[164:165], v[152:153]
	v_pk_mul_f32 v[148:149], v[164:165], v[200:201]
	v_pk_mul_f32 v[156:157], v[164:165], v[202:203]
	v_pk_mul_f32 v[158:159], v[164:165], v[158:159]
	v_pk_mul_f32 v[160:161], v[164:165], v[160:161]
	v_pk_mul_f32 v[154:155], v[164:165], v[204:205]
	v_pk_mul_f32 v[162:163], v[164:165], v[206:207]
	s_waitcnt lgkmcnt(7)
	v_add_f32_e32 v184, v184, v192
	s_waitcnt lgkmcnt(6)
	v_add_f32_e32 v185, v185, v193
	s_waitcnt lgkmcnt(5)
	v_add_f32_e32 v186, v186, v194
	s_waitcnt lgkmcnt(4)
	v_add_f32_e32 v187, v187, v195
	s_waitcnt lgkmcnt(3)
	v_add_f32_e32 v188, v188, v196
	s_waitcnt lgkmcnt(2)
	v_add_f32_e32 v189, v189, v197
	s_waitcnt lgkmcnt(1)
	v_add_f32_e32 v190, v190, v198
	s_waitcnt lgkmcnt(0)
	v_add_f32_e32 v191, v191, v199
	v_fmamk_f32 v184, v184, 0x3c800000, v178
	v_fmamk_f32 v185, v185, 0x3c800000, v178
	v_fmamk_f32 v186, v186, 0x3c800000, v178
	v_fmamk_f32 v187, v187, 0x3c800000, v178
	v_fmamk_f32 v188, v188, 0x3c800000, v178
	v_fmamk_f32 v189, v189, 0x3c800000, v178
	v_fmamk_f32 v190, v190, 0x3c800000, v178
	v_fmamk_f32 v191, v191, 0x3c800000, v178
	v_rsq_f32_e32 v184, v184
	v_rsq_f32_e32 v185, v185
	v_rsq_f32_e32 v186, v186
	v_rsq_f32_e32 v187, v187
	v_rsq_f32_e32 v188, v188
	v_rsq_f32_e32 v189, v189
	v_rsq_f32_e32 v190, v190
	v_rsq_f32_e32 v191, v191
	s_nop 0
	v_mul_f32_e32 v124, v124, v184
	v_mul_f32_e32 v125, v125, v184
	v_mul_f32_e32 v126, v126, v184
	v_mul_f32_e32 v127, v127, v184
	v_mul_f32_e32 v120, v120, v184
	v_mul_f32_e32 v121, v121, v184
	v_mul_f32_e32 v122, v122, v184
	v_mul_f32_e32 v123, v123, v184
	v_mul_f32_e32 v124, v124, v150
	v_mul_f32_e32 v125, v125, v151
	v_mul_f32_e32 v126, v126, v152
	v_mul_f32_e32 v127, v127, v153
	v_mul_f32_e32 v120, v120, v148
	v_mul_f32_e32 v121, v121, v149
	v_mul_f32_e32 v122, v122, v156
	v_mul_f32_e32 v123, v123, v157
	v_cvt_pk_bf16_f32 v230, v124, v125
	v_cvt_pk_bf16_f32 v231, v126, v127
	v_cvt_pk_bf16_f32 v232, v120, v121
	v_cvt_pk_bf16_f32 v233, v122, v123
	global_store_dwordx4 v240, v[230:233], s[72:73] nt
	v_mul_f32_e32 v116, v116, v184
	v_mul_f32_e32 v117, v117, v184
	v_mul_f32_e32 v118, v118, v184
	v_mul_f32_e32 v119, v119, v184
	v_mul_f32_e32 v112, v112, v184
	v_mul_f32_e32 v113, v113, v184
	v_mul_f32_e32 v114, v114, v184
	v_mul_f32_e32 v115, v115, v184
	v_mul_f32_e32 v116, v116, v158
	v_mul_f32_e32 v117, v117, v159
	v_mul_f32_e32 v118, v118, v160
	v_mul_f32_e32 v119, v119, v161
	v_mul_f32_e32 v112, v112, v154
	v_mul_f32_e32 v113, v113, v155
	v_mul_f32_e32 v114, v114, v162
	v_mul_f32_e32 v115, v115, v163
	v_cvt_pk_bf16_f32 v234, v116, v117
	v_cvt_pk_bf16_f32 v235, v118, v119
	v_cvt_pk_bf16_f32 v236, v112, v113
	v_cvt_pk_bf16_f32 v237, v114, v115
	global_store_dwordx4 v240, v[234:237], s[72:73] offset:64 nt
	v_mul_f32_e32 v108, v108, v185
	v_mul_f32_e32 v109, v109, v185
	v_mul_f32_e32 v110, v110, v185
	v_mul_f32_e32 v111, v111, v185
	v_mul_f32_e32 v104, v104, v185
	v_mul_f32_e32 v105, v105, v185
	v_mul_f32_e32 v106, v106, v185
	v_mul_f32_e32 v107, v107, v185
	v_mul_f32_e32 v108, v108, v150
	v_mul_f32_e32 v109, v109, v151
	v_mul_f32_e32 v110, v110, v152
	v_mul_f32_e32 v111, v111, v153
	v_mul_f32_e32 v104, v104, v148
	v_mul_f32_e32 v105, v105, v149
	v_mul_f32_e32 v106, v106, v156
	v_mul_f32_e32 v107, v107, v157
	v_cvt_pk_bf16_f32 v230, v108, v109
	v_cvt_pk_bf16_f32 v231, v110, v111
	v_cvt_pk_bf16_f32 v232, v104, v105
	v_cvt_pk_bf16_f32 v233, v106, v107
	v_add_u32_e32 v241, 0x10000, v240
	global_store_dwordx4 v241, v[230:233], s[72:73] nt
	v_mul_f32_e32 v100, v100, v185
	v_mul_f32_e32 v101, v101, v185
	v_mul_f32_e32 v102, v102, v185
	v_mul_f32_e32 v103, v103, v185
	v_mul_f32_e32 v96, v96, v185
	v_mul_f32_e32 v97, v97, v185
	v_mul_f32_e32 v98, v98, v185
	v_mul_f32_e32 v99, v99, v185
	v_mul_f32_e32 v100, v100, v158
	v_mul_f32_e32 v101, v101, v159
	v_mul_f32_e32 v102, v102, v160
	v_mul_f32_e32 v103, v103, v161
	v_mul_f32_e32 v96, v96, v154
	v_mul_f32_e32 v97, v97, v155
	v_mul_f32_e32 v98, v98, v162
	v_mul_f32_e32 v99, v99, v163
	v_cvt_pk_bf16_f32 v234, v100, v101
	v_cvt_pk_bf16_f32 v235, v102, v103
	v_cvt_pk_bf16_f32 v236, v96, v97
	v_cvt_pk_bf16_f32 v237, v98, v99
	global_store_dwordx4 v241, v[234:237], s[72:73] offset:64 nt
	v_mul_f32_e32 v92, v92, v186
	v_mul_f32_e32 v93, v93, v186
	v_mul_f32_e32 v94, v94, v186
	v_mul_f32_e32 v95, v95, v186
	v_mul_f32_e32 v88, v88, v186
	v_mul_f32_e32 v89, v89, v186
	v_mul_f32_e32 v90, v90, v186
	v_mul_f32_e32 v91, v91, v186
	v_mul_f32_e32 v92, v92, v150
	v_mul_f32_e32 v93, v93, v151
	v_mul_f32_e32 v94, v94, v152
	v_mul_f32_e32 v95, v95, v153
	v_mul_f32_e32 v88, v88, v148
	v_mul_f32_e32 v89, v89, v149
	v_mul_f32_e32 v90, v90, v156
	v_mul_f32_e32 v91, v91, v157
	v_cvt_pk_bf16_f32 v230, v92, v93
	v_cvt_pk_bf16_f32 v231, v94, v95
	v_cvt_pk_bf16_f32 v232, v88, v89
	v_cvt_pk_bf16_f32 v233, v90, v91
	v_add_u32_e32 v241, 0x20000, v240
	global_store_dwordx4 v241, v[230:233], s[72:73] nt
; __device__ __forceinline__ u32x4 pack8(const f32x4& a, const f32x4& b) { u32x4 w; w.x = pk2(a[0], a[1]); w.y = pk2(a[2], a[3]); w.z = pk2(b[0], b[1]); w.w = pk2(b[2], b[3]); return w; }
;     __device__ __forceinline__ void operator()(const AccT& acc, const Unit& u, int wr, int wc, int fr, int fq) const {
;     ...
;                 bf16_t* rp = base + (size_t)row * BR + tile * 256 + 64 * wc + 8 * fq;
; #pragma unroll
;                 for (int bj = 0; bj < 2; ++bj) { const f32x4 v0 = acc[ai][bj][m][0] * rs * gv[bj][0], v1 = acc[ai][bj][m][1] * rs * gv[bj][1];
;                     __builtin_nontemporal_store(pack8(v0, v1), (u32x4*)(rp + 32 * bj)); }
	v_mul_f32_e32 v84, v84, v186
	v_mul_f32_e32 v85, v85, v186
	v_mul_f32_e32 v86, v86, v186
	v_mul_f32_e32 v87, v87, v186
	v_mul_f32_e32 v80, v80, v186
	v_mul_f32_e32 v81, v81, v186
	v_mul_f32_e32 v82, v82, v186
	v_mul_f32_e32 v83, v83, v186
	v_mul_f32_e32 v84, v84, v158
	v_mul_f32_e32 v85, v85, v159
	v_mul_f32_e32 v86, v86, v160
	v_mul_f32_e32 v87, v87, v161
	v_mul_f32_e32 v80, v80, v154
	v_mul_f32_e32 v81, v81, v155
	v_mul_f32_e32 v82, v82, v162
	v_mul_f32_e32 v83, v83, v163
	v_cvt_pk_bf16_f32 v234, v84, v85
	v_cvt_pk_bf16_f32 v235, v86, v87
	v_cvt_pk_bf16_f32 v236, v80, v81
	v_cvt_pk_bf16_f32 v237, v82, v83
	global_store_dwordx4 v241, v[234:237], s[72:73] offset:64 nt
	v_mul_f32_e32 v76, v76, v187
	v_mul_f32_e32 v77, v77, v187
	v_mul_f32_e32 v78, v78, v187
	v_mul_f32_e32 v79, v79, v187
	v_mul_f32_e32 v72, v72, v187
	v_mul_f32_e32 v73, v73, v187
	v_mul_f32_e32 v74, v74, v187
	v_mul_f32_e32 v75, v75, v187
	v_mul_f32_e32 v76, v76, v150
	v_mul_f32_e32 v77, v77, v151
	v_mul_f32_e32 v78, v78, v152
	v_mul_f32_e32 v79, v79, v153
	v_mul_f32_e32 v72, v72, v148
	v_mul_f32_e32 v73, v73, v149
	v_mul_f32_e32 v74, v74, v156
	v_mul_f32_e32 v75, v75, v157
	v_cvt_pk_bf16_f32 v230, v76, v77
	v_cvt_pk_bf16_f32 v231, v78, v79
	v_cvt_pk_bf16_f32 v232, v72, v73
	v_cvt_pk_bf16_f32 v233, v74, v75
	v_add_u32_e32 v241, 0x30000, v240
	global_store_dwordx4 v241, v[230:233], s[72:73] nt
	v_mul_f32_e32 v68, v68, v187
	v_mul_f32_e32 v69, v69, v187
	v_mul_f32_e32 v70, v70, v187
	v_mul_f32_e32 v71, v71, v187
	v_mul_f32_e32 v64, v64, v187
	v_mul_f32_e32 v65, v65, v187
	v_mul_f32_e32 v66, v66, v187
	v_mul_f32_e32 v67, v67, v187
	v_mul_f32_e32 v68, v68, v158
	v_mul_f32_e32 v69, v69, v159
	v_mul_f32_e32 v70, v70, v160
	v_mul_f32_e32 v71, v71, v161
	v_mul_f32_e32 v64, v64, v154
	v_mul_f32_e32 v65, v65, v155
	v_mul_f32_e32 v66, v66, v162
	v_mul_f32_e32 v67, v67, v163
	v_cvt_pk_bf16_f32 v234, v68, v69
	v_cvt_pk_bf16_f32 v235, v70, v71
	v_cvt_pk_bf16_f32 v236, v64, v65
	v_cvt_pk_bf16_f32 v237, v66, v67
	global_store_dwordx4 v241, v[234:237], s[72:73] offset:64 nt
	v_mul_f32_e32 v60, v60, v188
	v_mul_f32_e32 v61, v61, v188
	v_mul_f32_e32 v62, v62, v188
	v_mul_f32_e32 v63, v63, v188
	v_mul_f32_e32 v56, v56, v188
	v_mul_f32_e32 v57, v57, v188
	v_mul_f32_e32 v58, v58, v188
	v_mul_f32_e32 v59, v59, v188
	v_mul_f32_e32 v60, v60, v150
	v_mul_f32_e32 v61, v61, v151
	v_mul_f32_e32 v62, v62, v152
	v_mul_f32_e32 v63, v63, v153
	v_mul_f32_e32 v56, v56, v148
	v_mul_f32_e32 v57, v57, v149
	v_mul_f32_e32 v58, v58, v156
	v_mul_f32_e32 v59, v59, v157
	v_cvt_pk_bf16_f32 v230, v60, v61
	v_cvt_pk_bf16_f32 v231, v62, v63
	v_cvt_pk_bf16_f32 v232, v56, v57
	v_cvt_pk_bf16_f32 v233, v58, v59
	v_add_u32_e32 v241, 0x80000, v240
	global_store_dwordx4 v241, v[230:233], s[72:73] nt
	v_mul_f32_e32 v52, v52, v188
	v_mul_f32_e32 v53, v53, v188
	v_mul_f32_e32 v54, v54, v188
	v_mul_f32_e32 v55, v55, v188
	v_mul_f32_e32 v48, v48, v188
	v_mul_f32_e32 v49, v49, v188
	v_mul_f32_e32 v50, v50, v188
	v_mul_f32_e32 v51, v51, v188
	v_mul_f32_e32 v52, v52, v158
	v_mul_f32_e32 v53, v53, v159
	v_mul_f32_e32 v54, v54, v160
	v_mul_f32_e32 v55, v55, v161
	v_mul_f32_e32 v48, v48, v154
	v_mul_f32_e32 v49, v49, v155
	v_mul_f32_e32 v50, v50, v162
	v_mul_f32_e32 v51, v51, v163
	v_cvt_pk_bf16_f32 v234, v52, v53
	v_cvt_pk_bf16_f32 v235, v54, v55
	v_cvt_pk_bf16_f32 v236, v48, v49
	v_cvt_pk_bf16_f32 v237, v50, v51
	global_store_dwordx4 v241, v[234:237], s[72:73] offset:64 nt
	v_mul_f32_e32 v44, v44, v189
	v_mul_f32_e32 v45, v45, v189
	v_mul_f32_e32 v46, v46, v189
	v_mul_f32_e32 v47, v47, v189
	v_mul_f32_e32 v40, v40, v189
	v_mul_f32_e32 v41, v41, v189
	v_mul_f32_e32 v42, v42, v189
	v_mul_f32_e32 v43, v43, v189
	v_mul_f32_e32 v44, v44, v150
	v_mul_f32_e32 v45, v45, v151
	v_mul_f32_e32 v46, v46, v152
	v_mul_f32_e32 v47, v47, v153
	v_mul_f32_e32 v40, v40, v148
	v_mul_f32_e32 v41, v41, v149
	v_mul_f32_e32 v42, v42, v156
	v_mul_f32_e32 v43, v43, v157
	v_cvt_pk_bf16_f32 v230, v44, v45
	v_cvt_pk_bf16_f32 v231, v46, v47
	v_cvt_pk_bf16_f32 v232, v40, v41
	v_cvt_pk_bf16_f32 v233, v42, v43
	v_add_u32_e32 v241, 0x90000, v240
	global_store_dwordx4 v241, v[230:233], s[72:73] nt
	v_mul_f32_e32 v36, v36, v189
	v_mul_f32_e32 v37, v37, v189
	v_mul_f32_e32 v38, v38, v189
	v_mul_f32_e32 v39, v39, v189
	v_mul_f32_e32 v32, v32, v189
	v_mul_f32_e32 v33, v33, v189
	v_mul_f32_e32 v34, v34, v189
	v_mul_f32_e32 v35, v35, v189
	v_mul_f32_e32 v36, v36, v158
	v_mul_f32_e32 v37, v37, v159
	v_mul_f32_e32 v38, v38, v160
	v_mul_f32_e32 v39, v39, v161
	v_mul_f32_e32 v32, v32, v154
	v_mul_f32_e32 v33, v33, v155
	v_mul_f32_e32 v34, v34, v162
	v_mul_f32_e32 v35, v35, v163
	v_cvt_pk_bf16_f32 v234, v36, v37
	v_cvt_pk_bf16_f32 v235, v38, v39
	v_cvt_pk_bf16_f32 v236, v32, v33
	v_cvt_pk_bf16_f32 v237, v34, v35
	global_store_dwordx4 v241, v[234:237], s[72:73] offset:64 nt
	v_mul_f32_e32 v28, v28, v190
	v_mul_f32_e32 v29, v29, v190
	v_mul_f32_e32 v30, v30, v190
	v_mul_f32_e32 v31, v31, v190
	v_mul_f32_e32 v24, v24, v190
	v_mul_f32_e32 v25, v25, v190
	v_mul_f32_e32 v26, v26, v190
	v_mul_f32_e32 v27, v27, v190
	v_mul_f32_e32 v28, v28, v150
	v_mul_f32_e32 v29, v29, v151
	v_mul_f32_e32 v30, v30, v152
	v_mul_f32_e32 v31, v31, v153
	v_mul_f32_e32 v24, v24, v148
	v_mul_f32_e32 v25, v25, v149
	v_mul_f32_e32 v26, v26, v156
	v_mul_f32_e32 v27, v27, v157
	v_cvt_pk_bf16_f32 v230, v28, v29
	v_cvt_pk_bf16_f32 v231, v30, v31
	v_cvt_pk_bf16_f32 v232, v24, v25
	v_cvt_pk_bf16_f32 v233, v26, v27
	v_add_u32_e32 v241, 0xa0000, v240
	global_store_dwordx4 v241, v[230:233], s[72:73] nt
	v_mul_f32_e32 v20, v20, v190
; __device__ __forceinline__ u32x4 pack8(const f32x4& a, const f32x4& b) { u32x4 w; w.x = pk2(a[0], a[1]); w.y = pk2(a[2], a[3]); w.z = pk2(b[0], b[1]); w.w = pk2(b[2], b[3]); return w; }
;     __device__ __forceinline__ void operator()(const AccT& acc, const Unit& u, int wr, int wc, int fr, int fq) const {
;     ...
;                 bf16_t* rp = base + (size_t)row * BR + tile * 256 + 64 * wc + 8 * fq;
; #pragma unroll
;                 for (int bj = 0; bj < 2; ++bj) { const f32x4 v0 = acc[ai][bj][m][0] * rs * gv[bj][0], v1 = acc[ai][bj][m][1] * rs * gv[bj][1];
;                     __builtin_nontemporal_store(pack8(v0, v1), (u32x4*)(rp + 32 * bj)); }
;             }
	v_mul_f32_e32 v21, v21, v190
	v_mul_f32_e32 v22, v22, v190
	v_mul_f32_e32 v23, v23, v190
	v_mul_f32_e32 v16, v16, v190
	v_mul_f32_e32 v17, v17, v190
	v_mul_f32_e32 v18, v18, v190
	v_mul_f32_e32 v19, v19, v190
	v_mul_f32_e32 v20, v20, v158
	v_mul_f32_e32 v21, v21, v159
	v_mul_f32_e32 v22, v22, v160
	v_mul_f32_e32 v23, v23, v161
	v_mul_f32_e32 v16, v16, v154
	v_mul_f32_e32 v17, v17, v155
	v_mul_f32_e32 v18, v18, v162
	v_mul_f32_e32 v19, v19, v163
	v_cvt_pk_bf16_f32 v234, v20, v21
	v_cvt_pk_bf16_f32 v235, v22, v23
	v_cvt_pk_bf16_f32 v236, v16, v17
	v_cvt_pk_bf16_f32 v237, v18, v19
	global_store_dwordx4 v241, v[234:237], s[72:73] offset:64 nt
	v_mul_f32_e32 v12, v12, v191
	v_mul_f32_e32 v13, v13, v191
	v_mul_f32_e32 v14, v14, v191
	v_mul_f32_e32 v15, v15, v191
	v_mul_f32_e32 v8, v8, v191
	v_mul_f32_e32 v9, v9, v191
	v_mul_f32_e32 v10, v10, v191
	v_mul_f32_e32 v11, v11, v191
	v_mul_f32_e32 v12, v12, v150
	v_mul_f32_e32 v13, v13, v151
	v_mul_f32_e32 v14, v14, v152
	v_mul_f32_e32 v15, v15, v153
	v_mul_f32_e32 v8, v8, v148
	v_mul_f32_e32 v9, v9, v149
	v_mul_f32_e32 v10, v10, v156
	v_mul_f32_e32 v11, v11, v157
	v_cvt_pk_bf16_f32 v230, v12, v13
	v_cvt_pk_bf16_f32 v231, v14, v15
	v_cvt_pk_bf16_f32 v232, v8, v9
	v_cvt_pk_bf16_f32 v233, v10, v11
	v_add_u32_e32 v241, 0xb0000, v240
	global_store_dwordx4 v241, v[230:233], s[72:73] nt
	v_mul_f32_e32 v4, v4, v191
	v_mul_f32_e32 v5, v5, v191
	v_mul_f32_e32 v6, v6, v191
	v_mul_f32_e32 v7, v7, v191
	v_mul_f32_e32 v0, v0, v191
	v_mul_f32_e32 v1, v1, v191
	v_mul_f32_e32 v2, v2, v191
	v_mul_f32_e32 v3, v3, v191
	v_mul_f32_e32 v4, v4, v158
	v_mul_f32_e32 v5, v5, v159
	v_mul_f32_e32 v6, v6, v160
	v_mul_f32_e32 v7, v7, v161
	v_mul_f32_e32 v0, v0, v154
	v_mul_f32_e32 v1, v1, v155
	v_mul_f32_e32 v2, v2, v162
	v_mul_f32_e32 v3, v3, v163
	v_cvt_pk_bf16_f32 v234, v4, v5
	v_cvt_pk_bf16_f32 v235, v6, v7
	v_cvt_pk_bf16_f32 v236, v0, v1
	v_cvt_pk_bf16_f32 v237, v2, v3
	global_store_dwordx4 v241, v[234:237], s[72:73] offset:64 nt
	s_branch .Lqkz_done_z
.Lqkz_plain_z:
	v_cvt_pk_bf16_f32 v230, v124, v125
	v_cvt_pk_bf16_f32 v231, v126, v127
	v_cvt_pk_bf16_f32 v232, v120, v121
	v_cvt_pk_bf16_f32 v233, v122, v123
	global_store_dwordx4 v240, v[230:233], s[72:73] nt
	v_cvt_pk_bf16_f32 v234, v116, v117
	v_cvt_pk_bf16_f32 v235, v118, v119
	v_cvt_pk_bf16_f32 v236, v112, v113
	v_cvt_pk_bf16_f32 v237, v114, v115
	global_store_dwordx4 v240, v[234:237], s[72:73] offset:64 nt
	v_cvt_pk_bf16_f32 v230, v108, v109
	v_cvt_pk_bf16_f32 v231, v110, v111
	v_cvt_pk_bf16_f32 v232, v104, v105
	v_cvt_pk_bf16_f32 v233, v106, v107
	v_add_u32_e32 v241, 0x10000, v240
	global_store_dwordx4 v241, v[230:233], s[72:73] nt
	v_cvt_pk_bf16_f32 v234, v100, v101
	v_cvt_pk_bf16_f32 v235, v102, v103
	v_cvt_pk_bf16_f32 v236, v96, v97
	v_cvt_pk_bf16_f32 v237, v98, v99
	global_store_dwordx4 v241, v[234:237], s[72:73] offset:64 nt
	v_cvt_pk_bf16_f32 v230, v92, v93
	v_cvt_pk_bf16_f32 v231, v94, v95
	v_cvt_pk_bf16_f32 v232, v88, v89
	v_cvt_pk_bf16_f32 v233, v90, v91
	v_add_u32_e32 v241, 0x20000, v240
	global_store_dwordx4 v241, v[230:233], s[72:73] nt
	v_cvt_pk_bf16_f32 v234, v84, v85
	v_cvt_pk_bf16_f32 v235, v86, v87
	v_cvt_pk_bf16_f32 v236, v80, v81
	v_cvt_pk_bf16_f32 v237, v82, v83
	global_store_dwordx4 v241, v[234:237], s[72:73] offset:64 nt
	v_cvt_pk_bf16_f32 v230, v76, v77
	v_cvt_pk_bf16_f32 v231, v78, v79
	v_cvt_pk_bf16_f32 v232, v72, v73
	v_cvt_pk_bf16_f32 v233, v74, v75
	v_add_u32_e32 v241, 0x30000, v240
	global_store_dwordx4 v241, v[230:233], s[72:73] nt
	v_cvt_pk_bf16_f32 v234, v68, v69
	v_cvt_pk_bf16_f32 v235, v70, v71
	v_cvt_pk_bf16_f32 v236, v64, v65
	v_cvt_pk_bf16_f32 v237, v66, v67
	global_store_dwordx4 v241, v[234:237], s[72:73] offset:64 nt
	v_cvt_pk_bf16_f32 v230, v60, v61
	v_cvt_pk_bf16_f32 v231, v62, v63
	v_cvt_pk_bf16_f32 v232, v56, v57
	v_cvt_pk_bf16_f32 v233, v58, v59
	v_add_u32_e32 v241, 0x80000, v240
	global_store_dwordx4 v241, v[230:233], s[72:73] nt
	v_cvt_pk_bf16_f32 v234, v52, v53
	v_cvt_pk_bf16_f32 v235, v54, v55
	v_cvt_pk_bf16_f32 v236, v48, v49
	v_cvt_pk_bf16_f32 v237, v50, v51
	global_store_dwordx4 v241, v[234:237], s[72:73] offset:64 nt
	v_cvt_pk_bf16_f32 v230, v44, v45
	v_cvt_pk_bf16_f32 v231, v46, v47
	v_cvt_pk_bf16_f32 v232, v40, v41
	v_cvt_pk_bf16_f32 v233, v42, v43
	v_add_u32_e32 v241, 0x90000, v240
	global_store_dwordx4 v241, v[230:233], s[72:73] nt
	v_cvt_pk_bf16_f32 v234, v36, v37
	v_cvt_pk_bf16_f32 v235, v38, v39
	v_cvt_pk_bf16_f32 v236, v32, v33
	v_cvt_pk_bf16_f32 v237, v34, v35
	global_store_dwordx4 v241, v[234:237], s[72:73] offset:64 nt
	v_cvt_pk_bf16_f32 v230, v28, v29
	v_cvt_pk_bf16_f32 v231, v30, v31
	v_cvt_pk_bf16_f32 v232, v24, v25
	v_cvt_pk_bf16_f32 v233, v26, v27
	v_add_u32_e32 v241, 0xa0000, v240
	global_store_dwordx4 v241, v[230:233], s[72:73] nt
	v_cvt_pk_bf16_f32 v234, v20, v21
	v_cvt_pk_bf16_f32 v235, v22, v23
	v_cvt_pk_bf16_f32 v236, v16, v17
	v_cvt_pk_bf16_f32 v237, v18, v19
	global_store_dwordx4 v241, v[234:237], s[72:73] offset:64 nt
	v_cvt_pk_bf16_f32 v230, v12, v13
	v_cvt_pk_bf16_f32 v231, v14, v15
	v_cvt_pk_bf16_f32 v232, v8, v9
	v_cvt_pk_bf16_f32 v233, v10, v11
	v_add_u32_e32 v241, 0xb0000, v240
	global_store_dwordx4 v241, v[230:233], s[72:73] nt
	v_cvt_pk_bf16_f32 v234, v4, v5
	v_cvt_pk_bf16_f32 v235, v6, v7
	v_cvt_pk_bf16_f32 v236, v0, v1
	v_cvt_pk_bf16_f32 v237, v2, v3
	global_store_dwordx4 v241, v[234:237], s[72:73] offset:64 nt
.Lqkz_done_z:
	s_andn2_b64 vcc, exec, s[8:9]
	s_mov_b64 s[6:7], -1
	s_cbranch_vccnz .LBB0_158
	s_andn2_b64 vcc, exec, s[10:11]
	s_cbranch_vccnz .LBB0_157
	s_barrier
	s_branch .LBB0_157
